# attnA half-B softmax segment shifted by 4 bytes (e64 encoding of one v_mov + one s_nop after the loop): code-placement trial
# speedup vs baseline: 1.0027x; 1.0027x over previous
; DI unsigned pk2(float a, float b) { hwf32x2 f = {a, b}; hwbf16x2 r = __builtin_convertvector(f, hwbf16x2); return __builtin_bit_cast(unsigned, r); }
; #define MFMA32(a, b, c) __builtin_amdgcn_mfma_f32_32x32x16_bf16((a), (b), (c), 0, 0, 0)
; template <int MODE>
; DI void attn_mfma(const Params& p, int l, int b, int hd, int qb, unsigned char* smem) {
;     ...
;     float mx = -1e30f;
; #pragma unroll
;     for (int mt = 0; mt < 2; ++mt)
; #pragma unroll
;       for (int i = 0; i < 16; ++i) mx = fmaxf(mx, S[mt][i]);
;     mx = fmaxf(mx, __shfl_xor(mx, 32));
;     const float zmx = mx * cexp;
;     if (__any(zmx > mrun + 8.f)) {
;       const float mnew = fmaxf(mrun, zmx);
;       const float alpha = __builtin_amdgcn_exp2f(mrun - mnew);
;       mrun = mnew;
;       lsum *= alpha;
;       const f32x2 al2 = {alpha, alpha};
; #pragma unroll
;       for (int vt = 0; vt < 2; ++vt)
; #pragma unroll
;         for (int i = 0; i < 8; ++i) {
;           f32x2 o = {O[vt][2 * i], O[vt][2 * i + 1]};
;           o = o * al2;
;           O[vt][2 * i] = o.x; O[vt][2 * i + 1] = o.y;
;         }
;     }
;     const f32x2 c2 = {cexp, cexp}, m2 = {mrun, mrun};
;     f32x2 ps2 = {0.f, 0.f};
;     unsigned pk[2][8];
; #pragma unroll
;     for (int mt = 0; mt < 2; ++mt)
; #pragma unroll
;       for (int i = 0; i < 8; ++i) {
;         f32x2 z = {S[mt][2 * i], S[mt][2 * i + 1]};
;         z = z * c2 - m2;
;         f32x2 pv = {__builtin_amdgcn_exp2f(z.x), __builtin_amdgcn_exp2f(z.y)};
;         ps2 = ps2 + pv;
;         pk[mt][i] = pk2(pv.x, pv.y);
;       }
;     lsum += ps2.x + ps2.y;
; #pragma unroll
;     for (int mt = 0; mt < 2; ++mt)
; #pragma unroll
;       for (int s = 0; s < 2; ++s) {
;         const uint4 pu = make_uint4(pk[mt][4 * s], pk[mt][4 * s + 1], pk[mt][4 * s + 2], pk[mt][4 * s + 3]);
;         const bf16x8 pf = __builtin_bit_cast(bf16x8, pu);
; #pragma unroll
;         for (int vt = 0; vt < 2; ++vt) {
;           const unsigned char* bp = sVc + (vt * 32 + r) * 136 + (mt * 32 + 16 * s + 4 * h2) * 2;
;           const uint2 lo = *(const uint2*)(bp);
;           const uint2 hi = *(const uint2*)(bp + 16);
;           const uint4 u = make_uint4(lo.x, lo.y, hi.x, hi.y);
;           O[vt] = MFMA32(__builtin_bit_cast(bf16x8, u), pf, O[vt]);
;         }
;       }
.Laa_nra:
	v_fma_f32 v80, v80, s8, -v140
	v_fma_f32 v81, v81, s8, -v140
	v_fma_f32 v82, v82, s8, -v140
	v_fma_f32 v83, v83, s8, -v140
	v_fma_f32 v84, v84, s8, -v140
	v_fma_f32 v85, v85, s8, -v140
	v_fma_f32 v86, v86, s8, -v140
	v_fma_f32 v87, v87, s8, -v140
	v_exp_f32_e32 v80, v80
	v_exp_f32_e32 v81, v81
	v_exp_f32_e32 v82, v82
	v_exp_f32_e32 v83, v83
	v_exp_f32_e32 v84, v84
	v_exp_f32_e32 v85, v85
	v_exp_f32_e32 v86, v86
	v_exp_f32_e32 v87, v87
	v_add_f32_e64 v148, v80, 0
	v_add_f32_e64 v149, v81, 0
	v_add_f32_e32 v148, v82, v148
	v_add_f32_e32 v149, v83, v149
	v_add_f32_e32 v148, v84, v148
	v_add_f32_e32 v149, v85, v149
	v_add_f32_e32 v148, v86, v148
	v_add_f32_e32 v149, v87, v149
	v_cvt_pk_bf16_f32 v80, v80, v81
	v_cvt_pk_bf16_f32 v81, v82, v83
	v_cvt_pk_bf16_f32 v82, v84, v85
	v_cvt_pk_bf16_f32 v83, v86, v87
	v_fma_f32 v88, v88, s8, -v140
	v_fma_f32 v89, v89, s8, -v140
	v_fma_f32 v90, v90, s8, -v140
	v_mfma_f32_32x32x16_bf16 v[16:31], v[204:207], v[80:83], v[16:31]
	v_fma_f32 v91, v91, s8, -v140
	v_fma_f32 v92, v92, s8, -v140
	v_fma_f32 v93, v93, s8, -v140
	v_fma_f32 v94, v94, s8, -v140
	v_fma_f32 v95, v95, s8, -v140
	v_exp_f32_e32 v88, v88
	v_exp_f32_e32 v89, v89
	v_exp_f32_e32 v90, v90
	v_exp_f32_e32 v91, v91
	v_exp_f32_e32 v92, v92
	v_exp_f32_e32 v93, v93
	v_exp_f32_e32 v94, v94
	v_mfma_f32_32x32x16_bf16 v[0:15], v[208:211], v[80:83], v[0:15]
	v_exp_f32_e32 v95, v95
	v_add_f32_e32 v148, v88, v148
	v_add_f32_e32 v149, v89, v149
	v_add_f32_e32 v148, v90, v148
	v_add_f32_e32 v149, v91, v149
	v_add_f32_e32 v148, v92, v148
	v_add_f32_e32 v149, v93, v149
	v_add_f32_e32 v148, v94, v148
	v_add_f32_e32 v149, v95, v149
	v_cvt_pk_bf16_f32 v88, v88, v89
	v_cvt_pk_bf16_f32 v89, v90, v91
	v_cvt_pk_bf16_f32 v90, v92, v93
	v_cvt_pk_bf16_f32 v91, v94, v95
	v_fma_f32 v64, v64, s8, -v140
	v_fma_f32 v65, v65, s8, -v140
	v_fma_f32 v66, v66, s8, -v140
	v_mfma_f32_32x32x16_bf16 v[16:31], v[212:215], v[88:91], v[16:31]
	v_fma_f32 v67, v67, s8, -v140
	v_fma_f32 v68, v68, s8, -v140
	v_fma_f32 v69, v69, s8, -v140
	v_fma_f32 v70, v70, s8, -v140
	v_fma_f32 v71, v71, s8, -v140
	v_exp_f32_e32 v64, v64
	v_exp_f32_e32 v65, v65
	v_exp_f32_e32 v66, v66
	v_exp_f32_e32 v67, v67
	v_exp_f32_e32 v68, v68
	v_exp_f32_e32 v69, v69
	v_exp_f32_e32 v70, v70
	v_mfma_f32_32x32x16_bf16 v[0:15], v[216:219], v[88:91], v[0:15]
	v_exp_f32_e32 v71, v71
	v_add_f32_e32 v148, v64, v148
	v_add_f32_e32 v149, v65, v149
	v_add_f32_e32 v148, v66, v148
	v_add_f32_e32 v149, v67, v149
	v_add_f32_e32 v148, v68, v148
	v_add_f32_e32 v149, v69, v149
	v_add_f32_e32 v148, v70, v148
	v_add_f32_e32 v149, v71, v149
	v_cvt_pk_bf16_f32 v84, v64, v65
	v_cvt_pk_bf16_f32 v85, v66, v67
	v_cvt_pk_bf16_f32 v86, v68, v69
	v_cvt_pk_bf16_f32 v87, v70, v71
	v_fma_f32 v72, v72, s8, -v140
	v_fma_f32 v73, v73, s8, -v140
	v_fma_f32 v74, v74, s8, -v140
	s_waitcnt lgkmcnt(0)
	v_mfma_f32_32x32x16_bf16 v[16:31], v[220:223], v[84:87], v[16:31]
	v_fma_f32 v75, v75, s8, -v140
	v_fma_f32 v76, v76, s8, -v140
	v_fma_f32 v77, v77, s8, -v140
	v_fma_f32 v78, v78, s8, -v140
	v_fma_f32 v79, v79, s8, -v140
	v_exp_f32_e32 v72, v72
	v_exp_f32_e32 v73, v73
	v_exp_f32_e32 v74, v74
	v_exp_f32_e32 v75, v75
	v_exp_f32_e32 v76, v76
	v_exp_f32_e32 v77, v77
	v_exp_f32_e32 v78, v78
	v_mfma_f32_32x32x16_bf16 v[0:15], v[224:227], v[84:87], v[0:15]
	v_exp_f32_e32 v79, v79
	v_add_f32_e32 v148, v72, v148
	v_add_f32_e32 v149, v73, v149
	v_add_f32_e32 v148, v74, v148
	v_add_f32_e32 v149, v75, v149
	v_add_f32_e32 v148, v76, v148
	v_add_f32_e32 v149, v77, v149
	v_add_f32_e32 v148, v78, v148
	v_add_f32_e32 v149, v79, v149
	v_cvt_pk_bf16_f32 v64, v72, v73
	v_cvt_pk_bf16_f32 v65, v74, v75
	v_cvt_pk_bf16_f32 v66, v76, v77
	v_cvt_pk_bf16_f32 v67, v78, v79
	v_add_f32_e32 v151, v148, v149
	v_add_f32_e32 v152, v200, v151
	v_mfma_f32_32x32x16_bf16 v[16:31], v[228:231], v[64:67], v[16:31]
	v_max3_f32 v150, v48, s5, v49
	v_max3_f32 v150, v150, v50, v51
	v_max3_f32 v150, v150, v52, v53
	v_max3_f32 v150, v150, v54, v55
	v_max3_f32 v150, v150, v56, v57
	v_max3_f32 v150, v150, v58, v59
	v_max3_f32 v150, v150, v60, v61
	v_max3_f32 v150, v150, v62, v63
	v_mfma_f32_32x32x16_bf16 v[0:15], v[232:235], v[64:67], v[0:15]
	v_max3_f32 v150, v150, v32, v33
	v_max3_f32 v150, v150, v34, v35
	v_max3_f32 v150, v150, v36, v37
	v_max3_f32 v150, v150, v38, v39
	v_max3_f32 v150, v150, v40, v41
	v_max3_f32 v150, v150, v42, v43
	v_max3_f32 v150, v150, v44, v45
	v_max3_f32 v150, v150, v46, v47
	v_mov_b32_e64 v151, v150
	s_nop 1
	v_permlane32_swap_b32_e32 v151, v150
	ds_read2_b64 v[204:207], v238 offset0:64 offset1:66
	ds_read2_b64 v[208:211], v239 offset0:96 offset1:98
	ds_read2_b64 v[212:215], v238 offset0:68 offset1:70
	ds_read2_b64 v[216:219], v239 offset0:100 offset1:102
	ds_read2_b64 v[220:223], v238 offset0:72 offset1:74
	ds_read2_b64 v[224:227], v239 offset0:104 offset1:106
	ds_read2_b64 v[228:231], v238 offset0:76 offset1:78
	ds_read2_b64 v[232:235], v239 offset0:108 offset1:110
	s_waitcnt lgkmcnt(8)
	v_max_f32_e32 v151, v151, v151
	v_max_f32_e32 v150, v150, v151
	v_mul_f32_e32 v150, 0x3e8293ee, v150
	v_cmp_gt_f32_e32 vcc, v150, v146
	s_cbranch_vccz .Laa_nrb
	v_max_f32_e32 v150, v150, v150
	v_max_f32_e32 v151, v140, v140
	v_max_f32_e32 v150, v151, v150
	v_sub_f32_e32 v151, v140, v150
	v_exp_f32_e32 v154, v151
	v_mov_b32_e32 v140, v150
	v_pk_mul_f32 v[16:17], v[16:17], v[154:155] op_sel_hi:[1,0]
	v_pk_mul_f32 v[18:19], v[18:19], v[154:155] op_sel_hi:[1,0]
	v_pk_mul_f32 v[20:21], v[20:21], v[154:155] op_sel_hi:[1,0]
	v_pk_mul_f32 v[22:23], v[22:23], v[154:155] op_sel_hi:[1,0]
	v_pk_mul_f32 v[24:25], v[24:25], v[154:155] op_sel_hi:[1,0]
	v_pk_mul_f32 v[26:27], v[26:27], v[154:155] op_sel_hi:[1,0]
	v_pk_mul_f32 v[28:29], v[28:29], v[154:155] op_sel_hi:[1,0]
	v_pk_mul_f32 v[30:31], v[30:31], v[154:155] op_sel_hi:[1,0]
	v_pk_mul_f32 v[0:1], v[0:1], v[154:155] op_sel_hi:[1,0]
	v_pk_mul_f32 v[2:3], v[2:3], v[154:155] op_sel_hi:[1,0]
	v_pk_mul_f32 v[4:5], v[4:5], v[154:155] op_sel_hi:[1,0]
	v_pk_mul_f32 v[6:7], v[6:7], v[154:155] op_sel_hi:[1,0]
	v_pk_mul_f32 v[8:9], v[8:9], v[154:155] op_sel_hi:[1,0]
	v_pk_mul_f32 v[10:11], v[10:11], v[154:155] op_sel_hi:[1,0]
	v_pk_mul_f32 v[12:13], v[12:13], v[154:155] op_sel_hi:[1,0]
	v_pk_mul_f32 v[14:15], v[14:15], v[154:155] op_sel_hi:[1,0]
	v_mul_f32_e32 v152, v152, v154

; template <int MODE>
; DI void attn_mfma(const Params& p, int l, int b, int hd, int qb, unsigned char* smem) {
;     ...
;   const float ltot = lsum + __shfl_xor(lsum, 32);
;   if (MODE == 0) {
;     const float lam_init = 0.8f - 0.6f * __expf(-0.3f * (float)l);
;     float s01 = 0.f, s23 = 0.f;
;     for (int i = 0; i < 32; ++i) {
;       s01 += p.diff_lam[l * 128 + i] * p.diff_lam[l * 128 + 32 + i];
;       s23 += p.diff_lam[l * 128 + 64 + i] * p.diff_lam[l * 128 + 96 + i];
;     }
;     const float lam = expf(s01) - expf(s23) + lam_init;
;     float* sO = (float*)smem;
;     const int ql = (wv & 1) * 32 + r;
;     __syncthreads();
.LBB0_586:
	v_readlane_b32 s0, v254, 25
	v_readlane_b32 s1, v254, 26
	s_nop 4
	s_nop 0
	global_load_dwordx4 v[44:47], v161, s[0:1] offset:48
	global_load_dwordx4 v[64:67], v161, s[0:1] offset:32
	global_load_dwordx4 v[80:83], v161, s[0:1] offset:16
	global_load_dwordx4 v[88:91], v161, s[0:1]
	global_load_dwordx4 v[56:59], v161, s[0:1] offset:176
	global_load_dwordx4 v[72:75], v161, s[0:1] offset:160
	global_load_dwordx4 v[84:87], v161, s[0:1] offset:144
	global_load_dwordx4 v[92:95], v161, s[0:1] offset:128
	global_load_dwordx4 v[108:111], v161, s[0:1] offset:304
	global_load_dwordx4 v[128:131], v161, s[0:1] offset:288
	global_load_dwordx4 v[144:147], v161, s[0:1] offset:272
	global_load_dwordx4 v[152:155], v161, s[0:1] offset:256
	global_load_dwordx4 v[120:123], v161, s[0:1] offset:432
	global_load_dwordx4 v[136:139], v161, s[0:1] offset:416
	global_load_dwordx4 v[148:151], v161, s[0:1] offset:400
	global_load_dwordx4 v[156:159], v161, s[0:1] offset:384
	global_load_dwordx4 v[32:35], v161, s[0:1] offset:112
	global_load_dwordx4 v[40:43], v161, s[0:1] offset:96
	global_load_dwordx4 v[52:55], v161, s[0:1] offset:80
	global_load_dwordx4 v[68:71], v161, s[0:1] offset:64
	global_load_dwordx4 v[36:39], v161, s[0:1] offset:240
	global_load_dwordx4 v[48:51], v161, s[0:1] offset:224
	global_load_dwordx4 v[60:63], v161, s[0:1] offset:208
	global_load_dwordx4 v[76:79], v161, s[0:1] offset:192
	global_load_dwordx4 v[96:99], v161, s[0:1] offset:368
	global_load_dwordx4 v[104:107], v161, s[0:1] offset:352
	global_load_dwordx4 v[116:119], v161, s[0:1] offset:336
	global_load_dwordx4 v[132:135], v161, s[0:1] offset:320
	global_load_dwordx4 v[100:103], v161, s[0:1] offset:496
	global_load_dwordx4 v[112:115], v161, s[0:1] offset:480
	global_load_dwordx4 v[124:127], v161, s[0:1] offset:464
	global_load_dwordx4 v[140:143], v161, s[0:1] offset:448
	ds_bpermute_b32 v160, v170, v200
	v_or_b32_e32 v198, v199, v198
	v_lshlrev_b32_e32 v171, 4, v171
	s_movk_i32 s0, 0x104
	v_cmp_eq_u32_e32 vcc, 1, v197
	s_waitcnt lgkmcnt(0)
	v_add_f32_e32 v160, v200, v160
	v_mad_u32_u24 v197, v198, s0, v171
	s_barrier
	s_and_saveexec_b64 s[0:1], vcc
	s_cbranch_execz .LBB0_588
; DI int crow(int reg, int h) { return (reg & 3) + 8 * (reg >> 2) + 4 * h; }
; template <int MODE>
; DI void attn_mfma(const Params& p, int l, int b, int hd, int qb, unsigned char* smem) {
;     ...
;     float s01 = 0.f, s23 = 0.f;
;     for (int i = 0; i < 32; ++i) {
;       s01 += p.diff_lam[l * 128 + i] * p.diff_lam[l * 128 + 32 + i];
;       s23 += p.diff_lam[l * 128 + 64 + i] * p.diff_lam[l * 128 + 96 + i];
;     }
;     const float lam = expf(s01) - expf(s23) + lam_init;
;     float* sO = (float*)smem;
;     const int ql = (wv & 1) * 32 + r;
;     __syncthreads();
;     if (mp == 1) {
;       const float i1 = lam / ltot;
; #pragma unroll
;       for (int vt = 0; vt < 2; ++vt)
; #pragma unroll
;         for (int i = 0; i < 16; ++i) sO[ql * 65 + vt * 32 + crow(i, h2)] = O[vt][i] * i1;
;     }
	s_waitcnt vmcnt(0)
	v_fma_f32 v152, v152, v156, 0
	v_fmac_f32_e32 v152, v153, v157
	v_fmac_f32_e32 v152, v154, v158
	v_fmac_f32_e32 v152, v155, v159
	v_fma_f32 v88, v88, v92, 0
	v_fmac_f32_e32 v152, v144, v148
	v_fmac_f32_e32 v88, v89, v93
	v_fmac_f32_e32 v152, v145, v149
	v_fmac_f32_e32 v88, v90, v94
	v_fmac_f32_e32 v152, v146, v150
	v_fmac_f32_e32 v88, v91, v95
	v_fmac_f32_e32 v152, v147, v151
	v_fmac_f32_e32 v88, v80, v84
	v_fmac_f32_e32 v152, v128, v136
	v_fmac_f32_e32 v88, v81, v85
	v_fmac_f32_e32 v152, v129, v137
	v_fmac_f32_e32 v88, v82, v86
	v_fmac_f32_e32 v152, v130, v138
	v_fmac_f32_e32 v88, v83, v87
	v_fmac_f32_e32 v152, v131, v139
	v_fmac_f32_e32 v88, v64, v72
	v_fmac_f32_e32 v152, v108, v120
	v_fmac_f32_e32 v88, v65, v73
	v_fmac_f32_e32 v152, v109, v121
	v_fmac_f32_e32 v88, v66, v74
	v_fmac_f32_e32 v152, v110, v122
	v_fmac_f32_e32 v88, v67, v75
	v_fmac_f32_e32 v152, v111, v123
	v_fmac_f32_e32 v88, v44, v56
	v_fmac_f32_e32 v152, v132, v140
	v_fmac_f32_e32 v88, v45, v57
	v_fmac_f32_e32 v152, v133, v141
	v_fmac_f32_e32 v88, v46, v58
	v_fmac_f32_e32 v152, v134, v142
	v_fmac_f32_e32 v88, v47, v59
	v_fmac_f32_e32 v152, v135, v143
	v_fmac_f32_e32 v88, v68, v76
	v_fmac_f32_e32 v152, v116, v124
	v_fmac_f32_e32 v88, v69, v77
	v_fmac_f32_e32 v152, v117, v125
	v_fmac_f32_e32 v88, v70, v78
	v_fmac_f32_e32 v152, v118, v126
	v_fmac_f32_e32 v88, v71, v79
	v_fmac_f32_e32 v152, v119, v127
	v_pk_mul_f32 v[104:105], v[104:105], v[112:113]
	v_fmac_f32_e32 v88, v52, v60
	v_add_f32_e32 v104, v152, v104
	v_fmac_f32_e32 v88, v53, v61
	v_add_f32_e32 v108, v104, v105
	v_pk_mul_f32 v[104:105], v[106:107], v[114:115]
	v_fmac_f32_e32 v88, v54, v62
	v_add_f32_e32 v104, v108, v104
	v_fmac_f32_e32 v88, v55, v63
	v_pk_mul_f32 v[40:41], v[40:41], v[48:49]
	v_add_f32_e32 v104, v104, v105
	v_pk_mul_f32 v[96:97], v[96:97], v[100:101]
	v_add_f32_e32 v40, v88, v40
	v_add_f32_e32 v96, v104, v96
	v_add_f32_e32 v44, v40, v41
	v_pk_mul_f32 v[40:41], v[42:43], v[50:51]
	v_add_f32_e32 v100, v96, v97
	v_pk_mul_f32 v[96:97], v[98:99], v[102:103]
	v_add_f32_e32 v40, v44, v40
	v_add_f32_e32 v96, v100, v96
	v_add_f32_e32 v40, v40, v41
	v_pk_mul_f32 v[32:33], v[32:33], v[36:37]
	v_add_f32_e32 v96, v96, v97
	v_add_f32_e32 v32, v40, v32
	v_add_f32_e32 v36, v32, v33
	v_mul_f32_e32 v32, 0x3fb8aa3b, v96
	s_mov_b32 s2, 0x3fb8aa3b
	v_fma_f32 v33, v96, s2, -v32
	v_rndne_f32_e32 v37, v32
	v_fmac_f32_e32 v33, 0x32a5705f, v96
	v_sub_f32_e32 v32, v32, v37
	v_add_f32_e32 v32, v32, v33
	v_exp_f32_e32 v40, v32
	v_pk_mul_f32 v[32:33], v[34:35], v[38:39]
	v_cvt_i32_f32_e32 v37, v37
	v_add_f32_e32 v32, v36, v32
	v_add_f32_e32 v32, v32, v33
	v_mul_f32_e32 v34, 0x3fb8aa3b, v32
	v_fma_f32 v35, v32, s2, -v34
	v_rndne_f32_e32 v36, v34
	v_fmac_f32_e32 v35, 0x32a5705f, v32
	v_sub_f32_e32 v34, v34, v36
	v_add_f32_e32 v34, v34, v35
	v_exp_f32_e32 v34, v34
	v_cvt_i32_f32_e32 v35, v36
	s_mov_b32 s2, 0xc2ce8ed0
	v_ldexp_f32 v33, v40, v37
	v_cmp_ngt_f32_e32 vcc, s2, v96
	s_mov_b32 s4, 0x42b17218
	v_ldexp_f32 v34, v34, v35
	v_cndmask_b32_e32 v33, 0, v33, vcc
	v_cmp_nlt_f32_e32 vcc, s4, v96
	s_nop 1
	v_cndmask_b32_e32 v33, v191, v33, vcc
	v_cmp_ngt_f32_e32 vcc, s2, v32
	s_nop 1
	v_cndmask_b32_e32 v34, 0, v34, vcc
	v_cmp_nlt_f32_e32 vcc, s4, v32
	s_nop 1
	v_cndmask_b32_e32 v32, v191, v34, vcc
	v_sub_f32_e32 v32, v32, v33
	v_add_f32_e32 v32, v168, v32
	v_div_scale_f32 v33, s[4:5], v160, v160, v32
	v_rcp_f32_e32 v34, v33
	s_nop 0
	v_fma_f32 v35, -v33, v34, 1.0
	v_fmac_f32_e32 v34, v35, v34
	v_div_scale_f32 v35, vcc, v32, v160, v32
	v_mul_f32_e32 v36, v35, v34
	v_fma_f32 v37, -v33, v36, v35
	v_fmac_f32_e32 v36, v37, v34
	v_fma_f32 v33, -v33, v36, v35
	v_div_fmas_f32 v33, v33, v34, v36
	v_div_fixup_f32 v32, v33, v160, v32
	v_pk_mul_f32 v[34:35], v[16:17], v[32:33] op_sel_hi:[1,0]
	ds_write2_b32 v197, v34, v35 offset1:1
	v_pk_mul_f32 v[34:35], v[18:19], v[32:33] op_sel_hi:[1,0]
	ds_write2_b32 v197, v34, v35 offset0:2 offset1:3
	v_pk_mul_f32 v[34:35], v[20:21], v[32:33] op_sel_hi:[1,0]
	ds_write2_b32 v197, v34, v35 offset0:8 offset1:9
	v_pk_mul_f32 v[34:35], v[22:23], v[32:33] op_sel_hi:[1,0]
	ds_write2_b32 v197, v34, v35 offset0:10 offset1:11
	v_pk_mul_f32 v[34:35], v[24:25], v[32:33] op_sel_hi:[1,0]
	ds_write2_b32 v197, v34, v35 offset0:16 offset1:17
	v_pk_mul_f32 v[34:35], v[26:27], v[32:33] op_sel_hi:[1,0]
	ds_write2_b32 v197, v34, v35 offset0:18 offset1:19
	v_pk_mul_f32 v[34:35], v[28:29], v[32:33] op_sel_hi:[1,0]
	ds_write2_b32 v197, v34, v35 offset0:24 offset1:25
	v_pk_mul_f32 v[34:35], v[30:31], v[32:33] op_sel_hi:[1,0]
	ds_write2_b32 v197, v34, v35 offset0:26 offset1:27
	v_pk_mul_f32 v[34:35], v[0:1], v[32:33] op_sel_hi:[1,0]
	ds_write2_b32 v197, v34, v35 offset0:32 offset1:33
	v_pk_mul_f32 v[34:35], v[2:3], v[32:33] op_sel_hi:[1,0]
	ds_write2_b32 v197, v34, v35 offset0:34 offset1:35
	v_pk_mul_f32 v[34:35], v[4:5], v[32:33] op_sel_hi:[1,0]
	ds_write2_b32 v197, v34, v35 offset0:40 offset1:41
	v_pk_mul_f32 v[34:35], v[6:7], v[32:33] op_sel_hi:[1,0]
	ds_write2_b32 v197, v34, v35 offset0:42 offset1:43
	v_pk_mul_f32 v[34:35], v[8:9], v[32:33] op_sel_hi:[1,0]
	ds_write2_b32 v197, v34, v35 offset0:48 offset1:49
	v_pk_mul_f32 v[34:35], v[10:11], v[32:33] op_sel_hi:[1,0]
	ds_write2_b32 v197, v34, v35 offset0:50 offset1:51
	v_pk_mul_f32 v[34:35], v[12:13], v[32:33] op_sel_hi:[1,0]
	v_pk_mul_f32 v[32:33], v[14:15], v[32:33] op_sel_hi:[1,0]
	ds_write2_b32 v197, v34, v35 offset0:56 offset1:57
	ds_write2_b32 v197, v32, v33 offset0:58 offset1:59
